# MoBA item loop keeps o in place (no per-step register copies); FFN-up conv weights of iterations 2/4 prefetched with 1/3 and issued before the epilogue barrier
# speedup vs baseline: 1.0206x; 1.0178x over previous
; #define LDS_FENCE() asm volatile("" ::: "memory")
; template <bool CAUSAL> __device__ __forceinline__ void moba_span(lbyte* kbuf, lbyte* vbuf, const bf16* Kh, const bf16* Vh, int kpos0, int nsub, const s16x8* qf, int tq, bool valid, int qlo, int qhi, ...
;     ...
;         load_k<4>(kf, kbuf, KP64, l31, h); load_v_tr<2>(vf, vbuf, lane); LDS_FENCE();
;         qk1<4>(s[0], kf, qf);
;         const int dmin = qlo - (key0 + 31), dmax = qhi - key0;
;         const int bmin = t5_bucket(dmin > 0 ? dmin : 0), bmax = t5_bucket(dmax > 0 ? dmax : 0);
;         if (!CAUSAL && bmax - bmin <= 1) {
;             const float t0 = tab[bmin], t1 = tab[bmax]; const int th1 = thr[bmax];
;             float mxr = s[0][0];
; #pragma unroll
;             for (int r = 1; r < 16; ++r) mxr = fmaxf(mxr, s[0][r]);
;             mxr = pair_max(mxr);
;             const float cL = valid ? 0.125f * LOG2E : 0.f, bL = valid ? t0 : -INFINITY, mx = valid ? mxr * (0.125f * LOG2E) + fmaxf(t0, t1) : -INFINITY;
;             const bool grow = mx > m + 8.0f; const float mn = grow ? mx : m, off = bL - mn, offB = off + (t1 - t0);
;             if (__any(grow)) { const float alpha = __builtin_amdgcn_exp2f(m - mn); l *= alpha; o[0] = o[0] * alpha; o[1] = o[1] * alpha; }
;             m = mn;
;             const int x1 = (bmax > bmin) ? tq - key0 - th1 : -0x40000000; f32x2_t sum2 = {0.f, 0.f};
; #pragma unroll
;             for (int r = 0; r < 16; r += 2) { const int kk = kkrow(r, h);
;                 const f32x2_t ob = {x1 >= kk ? offB : off, x1 >= kk + 1 ? offB : off}; f32x2_t v = {s[0][r], s[0][r + 1]}; v = v * (f32x2_t){cL, cL} + ob;
;                 const float e0 = __builtin_amdgcn_exp2f(v.x), e1 = __builtin_amdgcn_exp2f(v.y); s[0][r] = e0; s[0][r + 1] = e1; sum2 += (f32x2_t){e0, e1}; }
;             l += pair_sum(sum2.x + sum2.y);
;         } else {
;             float bb[16];
; #pragma unroll
;             for (int r = 0; r < 16; ++r) { int dist = tq - (key0 + kkrow(r, h)); dist = dist > 0 ? dist : 0; bb[r] = dtab[dist < MC_NDT - 1 ? dist : MC_NDT - 1]; }
;             LDS_FENCE();
; #pragma unroll
;             for (int r = 0; r < 16; ++r) { const int dist = tq - (key0 + kkrow(r, h)); const bool ok = valid && (!CAUSAL || dist >= 0); s[0][r] = ok ? s[0][r] * (0.125f * LOG2E) + bb[r] : -INFINITY; }
;             softmax_upd<1, 2>(s, m, l, o);
.LBB0_667:
	ds_read_b128 v[34:37], v252 offset:36864
	ds_read_b128 v[38:41], v252 offset:36896
	ds_read_b128 v[42:45], v252 offset:36928
	ds_read_b128 v[46:49], v252 offset:36960
	ds_read_b64_tr_b16 v[158:159], v253 offset:41472
	ds_read_b64_tr_b16 v[160:161], v253 offset:42048
	ds_read_b64_tr_b16 v[156:157], v253 offset:42112
	ds_read_b64_tr_b16 v[154:155], v253 offset:41536
	s_waitcnt lgkmcnt(7)
	v_mfma_f32_32x32x16_bf16 v[66:81], v[34:37], v[102:105], 0
	s_add_i32 s15, s14, s11
	s_sub_i32 s17, s15, 31
	s_max_i32 s23, s17, 16
	s_flbit_i32_b32 s24, s23
	s_lshl_b32 s24, s24, 1
	s_sub_i32 s26, 62, s24
	s_add_i32 s21, s15, 0xff
	s_max_i32 s15, s17, 0
	s_mul_i32 s23, s23, s23
	s_lshl_b32 s24, 2, s26
	s_waitcnt lgkmcnt(6)
	v_mfma_f32_32x32x16_bf16 v[66:81], v[38:41], v[110:113], v[66:81]
	s_cmp_ge_u32 s23, s24
	s_cselect_b64 s[24:25], -1, 0
	v_cndmask_b32_e64 v0, 0, 1, s[24:25]
	ds_read_b64_tr_b16 v[150:151], v253 offset:43776
	ds_read_b64_tr_b16 v[152:153], v253 offset:44352
	ds_read_b64_tr_b16 v[148:149], v253 offset:44416
	ds_read_b64_tr_b16 v[146:147], v253 offset:43840
	v_readfirstlane_b32 s23, v0
	s_or_b32 s23, s26, s23
	s_min_u32 s23, s23, 23
	s_add_i32 s23, s23, 8
	s_cmp_lt_i32 s17, 16
	s_waitcnt lgkmcnt(9)
	v_mfma_f32_32x32x16_bf16 v[66:81], v[42:45], v[114:117], v[66:81]
	s_cselect_b32 s15, s15, s23
	s_max_i32 s23, s21, 16
	s_flbit_i32_b32 s24, s23
	s_lshl_b32 s24, s24, 1
	s_sub_i32 s26, 62, s24
	s_max_i32 s17, s21, 0
	s_mul_i32 s23, s23, s23
	s_lshl_b32 s24, 2, s26
	s_cmp_ge_u32 s23, s24
	s_cselect_b64 s[24:25], -1, 0
	v_cndmask_b32_e64 v0, 0, 1, s[24:25]
	s_waitcnt lgkmcnt(8)
	v_mfma_f32_32x32x16_bf16 v[66:81], v[46:49], v[118:121], v[66:81]
	v_readfirstlane_b32 s23, v0
	s_or_b32 s23, s26, s23
	s_min_u32 s23, s23, 23
	s_add_i32 s23, s23, 8
	s_cmp_lt_i32 s21, 16
	s_cselect_b32 s17, s17, s23
	s_sub_i32 s21, s17, s15
	s_mov_b64 s[24:25], -1
	s_cmp_gt_i32 s21, 1
	v_add_f32_e32 v0, 0x41000000, v231
	s_cbranch_scc0 .LBB0_671
	v_add_u32_e32 v34, s11, v237
	v_med3_i32 v35, v34, 0, v239
	v_add_u32_e32 v36, -1, v34
	v_add_u32_e32 v37, -2, v34
	v_add_u32_e32 v38, -3, v34
	v_add_u32_e32 v39, -8, v34
	v_add_u32_e32 v40, -9, v34
	v_add_u32_e32 v41, -10, v34
	v_add_u32_e32 v42, -11, v34
	v_add_u32_e32 v43, -16, v34
	v_subrev_u32_e32 v44, 17, v34
	v_subrev_u32_e32 v45, 18, v34
	v_subrev_u32_e32 v46, 19, v34
	v_subrev_u32_e32 v47, 24, v34
	v_subrev_u32_e32 v48, 25, v34
	v_subrev_u32_e32 v49, 26, v34
	v_subrev_u32_e32 v34, 27, v34
	v_med3_i32 v36, v36, 0, v239
	v_med3_i32 v37, v37, 0, v239
	v_med3_i32 v38, v38, 0, v239
	v_med3_i32 v39, v39, 0, v239
	v_med3_i32 v40, v40, 0, v239
	v_med3_i32 v41, v41, 0, v239
	v_med3_i32 v42, v42, 0, v239
	v_med3_i32 v43, v43, 0, v239
	v_med3_i32 v44, v44, 0, v239
	v_med3_i32 v45, v45, 0, v239
	v_med3_i32 v46, v46, 0, v239
	v_med3_i32 v47, v47, 0, v239
	v_med3_i32 v48, v48, 0, v239
	v_med3_i32 v49, v49, 0, v239
	v_med3_i32 v34, v34, 0, v239
	v_lshl_add_u32 v35, v35, 2, s82
	v_lshl_add_u32 v36, v36, 2, s82
	v_lshl_add_u32 v37, v37, 2, s82
	v_lshl_add_u32 v38, v38, 2, s82
	v_lshl_add_u32 v39, v39, 2, s82
	v_lshl_add_u32 v40, v40, 2, s82
	v_lshl_add_u32 v41, v41, 2, s82
	v_lshl_add_u32 v42, v42, 2, s82
	v_lshl_add_u32 v43, v43, 2, s82
	v_lshl_add_u32 v44, v44, 2, s82
	v_lshl_add_u32 v45, v45, 2, s82
	v_lshl_add_u32 v46, v46, 2, s82
	v_lshl_add_u32 v47, v47, 2, s82
	v_lshl_add_u32 v48, v48, 2, s82
	v_lshl_add_u32 v49, v49, 2, s82
	v_lshl_add_u32 v34, v34, 2, s82
	ds_read_b32 v35, v35
	ds_read_b32 v36, v36
	ds_read_b32 v37, v37
	ds_read_b32 v38, v38
	ds_read_b32 v39, v39
	ds_read_b32 v40, v40
	ds_read_b32 v41, v41
	ds_read_b32 v42, v42
	ds_read_b32 v43, v43
	ds_read_b32 v44, v44
	ds_read_b32 v45, v45
	ds_read_b32 v46, v46
	ds_read_b32 v47, v47
	ds_read_b32 v48, v48
	ds_read_b32 v49, v49
	ds_read_b32 v34, v34
	s_waitcnt lgkmcnt(14)
	v_fmac_f32_e32 v35, 0x3e38aa3b, v66
	v_fmac_f32_e32 v36, 0x3e38aa3b, v67
	v_cndmask_b32_e64 v82, v238, v35, s[8:9]
	v_cndmask_b32_e64 v83, v238, v36, s[8:9]
	s_waitcnt lgkmcnt(13)
	v_fmac_f32_e32 v37, 0x3e38aa3b, v68
	s_waitcnt lgkmcnt(12)
	v_fmac_f32_e32 v38, 0x3e38aa3b, v69
	s_waitcnt lgkmcnt(0)
	v_fmac_f32_e32 v34, 0x3e38aa3b, v81
	v_cndmask_b32_e64 v84, v238, v37, s[8:9]
	v_cndmask_b32_e64 v85, v238, v38, s[8:9]
	v_fmac_f32_e32 v39, 0x3e38aa3b, v70
	v_fmac_f32_e32 v40, 0x3e38aa3b, v71
	v_cndmask_b32_e64 v97, v238, v34, s[8:9]
	v_max_f32_e32 v34, v82, v83
	v_cndmask_b32_e64 v86, v238, v39, s[8:9]
	v_cndmask_b32_e64 v87, v238, v40, s[8:9]
	v_fmac_f32_e32 v41, 0x3e38aa3b, v72
	v_fmac_f32_e32 v42, 0x3e38aa3b, v73
	v_max3_f32 v34, v34, v84, v85
	v_cndmask_b32_e64 v88, v238, v41, s[8:9]
	v_cndmask_b32_e64 v89, v238, v42, s[8:9]
	v_fmac_f32_e32 v43, 0x3e38aa3b, v74
	v_fmac_f32_e32 v44, 0x3e38aa3b, v75
	v_max3_f32 v34, v34, v86, v87
	v_cndmask_b32_e64 v90, v238, v43, s[8:9]
	v_cndmask_b32_e64 v91, v238, v44, s[8:9]
	v_fmac_f32_e32 v45, 0x3e38aa3b, v76
	v_fmac_f32_e32 v46, 0x3e38aa3b, v77
	v_max3_f32 v34, v34, v88, v89
	v_cndmask_b32_e64 v92, v238, v45, s[8:9]
	v_cndmask_b32_e64 v93, v238, v46, s[8:9]
	v_fmac_f32_e32 v47, 0x3e38aa3b, v78
	v_fmac_f32_e32 v48, 0x3e38aa3b, v79
	v_max3_f32 v34, v34, v90, v91
	v_cndmask_b32_e64 v94, v238, v47, s[8:9]
	v_cndmask_b32_e64 v95, v238, v48, s[8:9]
	v_fmac_f32_e32 v49, 0x3e38aa3b, v80
	v_max3_f32 v34, v34, v92, v93
	v_cndmask_b32_e64 v96, v238, v49, s[8:9]
	v_max3_f32 v34, v34, v94, v95
	v_max3_f32 v34, v34, v96, v97
	v_mov_b32_e32 v35, v34
	s_nop 1
	v_permlane32_swap_b32_e32 v34, v35
	v_max_f32_e32 v35, v35, v35
	v_max_f32_e32 v34, v34, v34
	v_max_f32_e32 v34, v34, v35
	v_cmp_gt_f32_e32 vcc, v34, v0
	v_mov_b32_e32 v162, v195
	s_nop 0
	v_cndmask_b32_e32 v194, v231, v34, vcc
	s_cbranch_vccz .LBB0_670
	v_sub_f32_e32 v34, v231, v194
	v_exp_f32_e32 v34, v34
	s_nop 0
	v_mul_f32_e32 v162, v195, v34
	v_pk_mul_f32 v[32:33], v[32:33], v[34:35] op_sel_hi:[1,0]
	v_pk_mul_f32 v[30:31], v[30:31], v[34:35] op_sel_hi:[1,0]
	v_pk_mul_f32 v[28:29], v[28:29], v[34:35] op_sel_hi:[1,0]
	v_pk_mul_f32 v[26:27], v[26:27], v[34:35] op_sel_hi:[1,0]
	v_pk_mul_f32 v[24:25], v[24:25], v[34:35] op_sel_hi:[1,0]
	v_pk_mul_f32 v[22:23], v[22:23], v[34:35] op_sel_hi:[1,0]
	v_pk_mul_f32 v[20:21], v[20:21], v[34:35] op_sel_hi:[1,0]
	v_pk_mul_f32 v[16:17], v[16:17], v[34:35] op_sel_hi:[1,0]
	v_pk_mul_f32 v[14:15], v[14:15], v[34:35] op_sel_hi:[1,0]
	v_pk_mul_f32 v[12:13], v[12:13], v[34:35] op_sel_hi:[1,0]
	v_pk_mul_f32 v[10:11], v[10:11], v[34:35] op_sel_hi:[1,0]
	v_pk_mul_f32 v[8:9], v[8:9], v[34:35] op_sel_hi:[1,0]
	v_pk_mul_f32 v[6:7], v[6:7], v[34:35] op_sel_hi:[1,0]
	v_pk_mul_f32 v[4:5], v[4:5], v[34:35] op_sel_hi:[1,0]
	v_pk_mul_f32 v[18:19], v[18:19], v[34:35] op_sel_hi:[1,0]
	v_pk_mul_f32 v[2:3], v[2:3], v[34:35] op_sel_hi:[1,0]

; __device__ __forceinline__ void pack_p_nat(const f32x16& s, s16x8& p0, s16x8& p1) {
;     unsigned a0 = pk2(s[0], s[1]), a1 = pk2(s[2], s[3]), b0 = pk2(s[4], s[5]), b1 = pk2(s[6], s[7]);
;     unsigned c0 = pk2(s[8], s[9]), c1 = pk2(s[10], s[11]), d0 = pk2(s[12], s[13]), d1 = pk2(s[14], s[15]);
; template <bool CAUSAL> __device__ __forceinline__ void moba_span(lbyte* kbuf, lbyte* vbuf, const bf16* Kh, const bf16* Vh, int kpos0, int nsub, const s16x8* qf, int tq, bool valid, int qlo, int qhi, ...
;     ...
;         if (!CAUSAL && bmax - bmin <= 1) {
;             const float t0 = tab[bmin], t1 = tab[bmax]; const int th1 = thr[bmax];
;             float mxr = s[0][0];
; #pragma unroll
;             for (int r = 1; r < 16; ++r) mxr = fmaxf(mxr, s[0][r]);
;             mxr = pair_max(mxr);
;             const float cL = valid ? 0.125f * LOG2E : 0.f, bL = valid ? t0 : -INFINITY, mx = valid ? mxr * (0.125f * LOG2E) + fmaxf(t0, t1) : -INFINITY;
;             const bool grow = mx > m + 8.0f; const float mn = grow ? mx : m, off = bL - mn, offB = off + (t1 - t0);
;             if (__any(grow)) { const float alpha = __builtin_amdgcn_exp2f(m - mn); l *= alpha; o[0] = o[0] * alpha; o[1] = o[1] * alpha; }
;             m = mn;
;             const int x1 = (bmax > bmin) ? tq - key0 - th1 : -0x40000000; f32x2_t sum2 = {0.f, 0.f};
; #pragma unroll
;             for (int r = 0; r < 16; r += 2) { const int kk = kkrow(r, h);
;                 const f32x2_t ob = {x1 >= kk ? offB : off, x1 >= kk + 1 ? offB : off}; f32x2_t v = {s[0][r], s[0][r + 1]}; v = v * (f32x2_t){cL, cL} + ob;
;                 const float e0 = __builtin_amdgcn_exp2f(v.x), e1 = __builtin_amdgcn_exp2f(v.y); s[0][r] = e0; s[0][r + 1] = e1; sum2 += (f32x2_t){e0, e1}; }
;             l += pair_sum(sum2.x + sum2.y);
;         } else {
;             float bb[16];
; #pragma unroll
;             for (int r = 0; r < 16; ++r) { int dist = tq - (key0 + kkrow(r, h)); dist = dist > 0 ? dist : 0; bb[r] = dtab[dist < MC_NDT - 1 ? dist : MC_NDT - 1]; }
;             LDS_FENCE();
; #pragma unroll
;             for (int r = 0; r < 16; ++r) { const int dist = tq - (key0 + kkrow(r, h)); const bool ok = valid && (!CAUSAL || dist >= 0); s[0][r] = ok ? s[0][r] * (0.125f * LOG2E) + bb[r] : -INFINITY; }
;             softmax_upd<1, 2>(s, m, l, o);
;         }
;         s16x8 p0, p1; pack_p_nat(s[0], p0, p1); pv1<2>(o, vf, p0, p1);
.LBB0_671:
	s_and_b64 vcc, exec, s[24:25]
	s_cbranch_vccz .LBB0_675
	s_lshl_b32 s21, s15, 2
	s_add_i32 s23, 0, 0x23f50
	s_add_i32 s21, s23, s21
	v_mov_b32_e32 v34, s21
	s_lshl_b32 s21, s17, 2
	s_add_i32 s23, s23, s21
	s_add_i32 s21, s21, 0
	s_add_i32 s21, s21, 0x23fd0
	v_mov_b32_e32 v36, s23
	v_mov_b32_e32 v37, s21
	ds_read_b32 v35, v34
	ds_read_b32 v36, v36
	ds_read_b32 v34, v37
	v_max_f32_e32 v37, v67, v67
	v_max_f32_e32 v38, v66, v66
	v_max_f32_e32 v37, v38, v37
	v_max3_f32 v37, v37, v68, v69
	v_max3_f32 v37, v37, v70, v71
	v_max3_f32 v37, v37, v72, v73
	v_max3_f32 v37, v37, v74, v75
	v_max3_f32 v37, v37, v76, v77
	v_max3_f32 v37, v37, v78, v79
	v_max3_f32 v37, v37, v80, v81
	v_mov_b32_e32 v38, v37
	s_nop 1
	v_permlane32_swap_b32_e32 v37, v38
	v_max_f32_e32 v38, v38, v38
	v_max_f32_e32 v37, v37, v37
	v_max_f32_e32 v37, v37, v38
	s_waitcnt lgkmcnt(1)
	v_max_f32_e32 v38, v36, v36
	v_max_f32_e32 v39, v35, v35
	v_max_f32_e32 v38, v39, v38
	v_fmac_f32_e32 v38, 0x3e38aa3b, v37
	v_cndmask_b32_e64 v37, v238, v38, s[8:9]
	v_cmp_gt_f32_e32 vcc, v37, v0
	s_nop 1
	v_cndmask_b32_e32 v194, v231, v37, vcc
	s_cbranch_vccz .LBB0_674
	v_sub_f32_e32 v0, v231, v194
	v_exp_f32_e32 v0, v0
	s_nop 0
	v_mul_f32_e32 v195, v195, v0
	v_pk_mul_f32 v[32:33], v[32:33], v[0:1] op_sel_hi:[1,0]
	v_pk_mul_f32 v[30:31], v[30:31], v[0:1] op_sel_hi:[1,0]
	v_pk_mul_f32 v[28:29], v[28:29], v[0:1] op_sel_hi:[1,0]
	v_pk_mul_f32 v[26:27], v[26:27], v[0:1] op_sel_hi:[1,0]
	v_pk_mul_f32 v[24:25], v[24:25], v[0:1] op_sel_hi:[1,0]
	v_pk_mul_f32 v[22:23], v[22:23], v[0:1] op_sel_hi:[1,0]
	v_pk_mul_f32 v[20:21], v[20:21], v[0:1] op_sel_hi:[1,0]
	v_pk_mul_f32 v[16:17], v[16:17], v[0:1] op_sel_hi:[1,0]
	v_pk_mul_f32 v[14:15], v[14:15], v[0:1] op_sel_hi:[1,0]
	v_pk_mul_f32 v[12:13], v[12:13], v[0:1] op_sel_hi:[1,0]
	v_pk_mul_f32 v[10:11], v[10:11], v[0:1] op_sel_hi:[1,0]
	v_pk_mul_f32 v[8:9], v[8:9], v[0:1] op_sel_hi:[1,0]
	v_pk_mul_f32 v[6:7], v[6:7], v[0:1] op_sel_hi:[1,0]
	v_pk_mul_f32 v[4:5], v[4:5], v[0:1] op_sel_hi:[1,0]
	v_pk_mul_f32 v[18:19], v[18:19], v[0:1] op_sel_hi:[1,0]
	v_pk_mul_f32 v[2:3], v[2:3], v[0:1] op_sel_hi:[1,0]
.LBB0_674:
	s_cmp_gt_u32 s17, s15
	s_waitcnt lgkmcnt(0)
	v_sub_u32_e32 v34, s11, v34
	v_cndmask_b32_e64 v0, v238, v35, s[8:9]
	v_add_u32_e32 v34, v34, v235
	s_cselect_b64 vcc, -1, 0
	v_sub_f32_e32 v0, v0, v194
	v_sub_f32_e32 v35, v36, v35
	v_cndmask_b32_e32 v39, -2.0, v34, vcc
	v_add_f32_e32 v38, v35, v0
	v_cmp_lt_i32_e32 vcc, v39, v241
	v_mov_b32_e32 v162, v195
	s_nop 0
	v_cndmask_b32_e32 v34, v38, v0, vcc
	v_cmp_gt_i32_e32 vcc, v39, v241
	s_nop 1
	v_cndmask_b32_e32 v35, v0, v38, vcc
	v_pk_fma_f32 v[34:35], v[196:197], v[66:67], v[34:35]
	v_cmp_lt_i32_e32 vcc, v39, v243
	v_exp_f32_e32 v82, v34
	v_exp_f32_e32 v83, v35
	v_cndmask_b32_e32 v34, v38, v0, vcc
	v_cmp_gt_i32_e32 vcc, v39, v243
	s_nop 1
	v_cndmask_b32_e32 v35, v0, v38, vcc
	v_pk_fma_f32 v[34:35], v[196:197], v[68:69], v[34:35]
	v_cmp_lt_i32_e32 vcc, v39, v244
	v_exp_f32_e32 v84, v34
	v_exp_f32_e32 v85, v35
	v_cndmask_b32_e32 v34, v38, v0, vcc
	v_cmp_gt_i32_e32 vcc, v39, v244
	s_nop 1
	v_cndmask_b32_e32 v35, v0, v38, vcc
	v_pk_fma_f32 v[34:35], v[196:197], v[70:71], v[34:35]
	v_cmp_lt_i32_e32 vcc, v39, v245
	v_exp_f32_e32 v86, v34
	v_exp_f32_e32 v87, v35
	v_cndmask_b32_e32 v34, v38, v0, vcc
	v_cmp_gt_i32_e32 vcc, v39, v245
	s_nop 1
	v_cndmask_b32_e32 v35, v0, v38, vcc
	v_cmp_lt_i32_e32 vcc, v39, v246
	v_pk_fma_f32 v[34:35], v[196:197], v[72:73], v[34:35]
	s_nop 0
	v_cndmask_b32_e32 v36, v38, v0, vcc
	v_cmp_gt_i32_e32 vcc, v39, v246
	v_exp_f32_e32 v88, v34
	v_exp_f32_e32 v89, v35
	v_cndmask_b32_e32 v37, v0, v38, vcc
	v_pk_fma_f32 v[36:37], v[196:197], v[74:75], v[36:37]
	v_cmp_lt_i32_e32 vcc, v39, v247
	v_exp_f32_e32 v90, v36
	v_exp_f32_e32 v91, v37
	v_cndmask_b32_e32 v36, v38, v0, vcc
	v_cmp_gt_i32_e32 vcc, v39, v247
	v_pk_add_f32 v[34:35], v[82:83], 0 op_sel_hi:[1,0]
	s_nop 0
	v_cndmask_b32_e32 v37, v0, v38, vcc
	v_pk_fma_f32 v[36:37], v[196:197], v[76:77], v[36:37]
	v_cmp_lt_i32_e32 vcc, v39, v248
	v_exp_f32_e32 v92, v36
	v_exp_f32_e32 v93, v37
	v_cndmask_b32_e32 v36, v38, v0, vcc
	v_cmp_gt_i32_e32 vcc, v39, v248
	v_pk_add_f32 v[34:35], v[84:85], v[34:35]
	s_nop 0
	v_cndmask_b32_e32 v37, v0, v38, vcc
	v_pk_fma_f32 v[36:37], v[196:197], v[78:79], v[36:37]
	v_cmp_lt_i32_e32 vcc, v39, v249
	v_exp_f32_e32 v94, v36
	v_exp_f32_e32 v95, v37
	v_cndmask_b32_e32 v36, v38, v0, vcc
	v_cmp_gt_i32_e32 vcc, v39, v249
	v_pk_add_f32 v[34:35], v[86:87], v[34:35]
	s_nop 0
	v_cndmask_b32_e32 v37, v0, v38, vcc
	v_pk_fma_f32 v[36:37], v[196:197], v[80:81], v[36:37]
	v_pk_add_f32 v[34:35], v[88:89], v[34:35]
	v_exp_f32_e32 v96, v36
	v_exp_f32_e32 v97, v37
	v_pk_add_f32 v[34:35], v[90:91], v[34:35]
	s_nop 0
	v_pk_add_f32 v[34:35], v[92:93], v[34:35]
	s_nop 0
	v_pk_add_f32 v[34:35], v[94:95], v[34:35]
	s_nop 0
	v_pk_add_f32 v[34:35], v[96:97], v[34:35]
	s_nop 0
	v_pk_add_f32 v[230:231], v[34:35], v[34:35] op_sel:[0,1] op_sel_hi:[1,0]
	v_mov_b32_e32 v163, v230
	s_nop 1
	v_permlane32_swap_b32_e32 v230, v163
.LBB0_675:
	v_cvt_pk_bf16_f32 v34, v82, v83
	v_cvt_pk_bf16_f32 v35, v84, v85
	v_cvt_pk_bf16_f32 v36, v86, v87
	v_cvt_pk_bf16_f32 v37, v88, v89
	s_nop 0
	v_permlane32_swap_b32_e32 v34, v36
	v_permlane32_swap_b32_e32 v35, v37
	v_cvt_pk_bf16_f32 v66, v90, v91
	s_waitcnt lgkmcnt(6)
	v_mfma_f32_32x32x16_bf16 v[2:17], v[158:161], v[34:37], v[2:17]
	v_cvt_pk_bf16_f32 v67, v92, v93
	v_cvt_pk_bf16_f32 v68, v94, v95
	v_cvt_pk_bf16_f32 v69, v96, v97
	s_nop 0
	v_permlane32_swap_b32_e32 v66, v68
	v_permlane32_swap_b32_e32 v67, v69
	s_waitcnt lgkmcnt(4)
	v_mfma_f32_32x32x16_bf16 v[18:33], v[154:157], v[34:37], v[18:33]
	s_nop 3
	s_nop 0
	s_waitcnt lgkmcnt(2)
	v_mfma_f32_32x32x16_bf16 v[2:17], v[150:153], v[66:69], v[2:17]
	v_add_f32_e32 v0, v230, v163
	s_sub_i32 s11, s11, 32
	s_add_i32 s22, s22, 32
	v_add_f32_e32 v195, v162, v0
	s_cmpk_lg_i32 s11, 0xff00
	s_waitcnt lgkmcnt(0)
	v_mfma_f32_32x32x16_bf16 v[18:33], v[146:149], v[66:69], v[18:33]
	s_cbranch_scc0 .LBB0_677
	v_mov_b32_e32 v231, v194
	s_nop 2
	s_branch .LBB0_665

; #define PG8_LAS __attribute__((address_space(3)))
; #define EPI_BAR() do { asm volatile("s_waitcnt lgkmcnt(0)" ::: "memory"); __builtin_amdgcn_s_barrier(); asm volatile("" ::: "memory"); } while (0)
;     __device__ __forceinline__ void operator()(f32x4 (&acc)[2][2][4][2], const Unit& u, int ui, int wr, int wc, int fr_, int fq_) const {
;     ...
;                 for (int bj = 0; bj < 2; ++bj)
; #pragma unroll
;                     for (int n = 0; n < 2; ++n) *(PG8_LAS f32x4*)(exch + (((2 * ai + wr) * 2 + (fr - 14)) * 256 + bj * HALF + 32 * wc + 8 * fq + 4 * n)) = acc[ai][bj][3][n];
;         }
;         EPI_BAR();
; #pragma unroll
;         for (int bj = 0; bj < 2; ++bj)
; #pragma unroll
;             for (int n = 0; n < 2; ++n) { const int ch = bj * 2816 + fbase + 4 * n;
;                 const f32x4 w0 = *(const f32x4*)(cw + ch), w1 = *(const f32x4*)(cw + 5632 + ch), w2 = *(const f32x4*)(cw + 2 * 5632 + ch), bb = *(const f32x4*)(cb + ch);
.LBB0_1184:
	s_or_b64 exec, exec, s[8:9]
	v_lshlrev_b64 v[30:31], 2, v[186:187]
	v_lshl_add_u64 v[204:205], s[44:45], 0, v[30:31]
	v_lshl_add_u64 v[200:201], s[22:23], 0, v[30:31]
	v_lshl_add_u64 v[198:199], s[46:47], 0, v[30:31]
	v_lshl_add_u64 v[202:203], s[20:21], 0, v[30:31]
	global_load_dwordx4 v[134:137], v[204:205], off
	global_load_dwordx4 v[118:121], v[202:203], off
	global_load_dwordx4 v[130:133], v[200:201], off
	global_load_dwordx4 v[234:237], v[204:205], off offset:16
	global_load_dwordx4 v[240:243], v[202:203], off offset:16
	global_load_dwordx4 v[244:247], v[200:201], off offset:16
	global_load_dwordx4 v[248:251], v[198:199], off offset:16
	global_load_dwordx4 v[30:33], v[198:199], off
	s_waitcnt lgkmcnt(0)
	s_barrier
	v_cndmask_b32_e64 v144, 0, 1, s[52:53]
	v_mov_b32_e32 v142, 0
	v_cmp_ne_u32_e64 s[10:11], 1, v144
	s_andn2_b64 vcc, exec, s[52:53]
	v_mov_b32_e32 v144, 0
	v_mov_b32_e32 v145, 0
	v_mov_b32_e32 v146, 0
	v_mov_b32_e32 v147, 0
	v_mov_b32_e32 v148, 0
	v_mov_b32_e32 v149, 0
	v_mov_b32_e32 v150, 0
	v_mov_b32_e32 v151, 0
	s_cbranch_vccnz .LBB0_1186
	v_add_u32_e32 v148, s62, v228
	v_add_u32_e32 v144, s31, v228
	ds_read_b128 v[144:147], v144
	ds_read_b128 v[148:151], v148

; #define PG8_LAS __attribute__((address_space(3)))
;     __device__ __forceinline__ void operator()(f32x4 (&acc)[2][2][4][2], const Unit& u, int ui, int wr, int wc, int fr_, int fq_) const {
;     ...
;             for (int n = 0; n < 2; ++n) { const int ch = bj * 2816 + fbase + 4 * n;
;                 const f32x4 w0 = *(const f32x4*)(cw + ch), w1 = *(const f32x4*)(cw + 5632 + ch), w2 = *(const f32x4*)(cw + 2 * 5632 + ch), bb = *(const f32x4*)(cb + ch);
; #pragma unroll
;                 for (int ai = 0; ai < 2; ++ai) { const int kb = 2 * ai + wr;
;                     f32x4 c62 = (f32x4){0.f, 0.f, 0.f, 0.f}, c63 = c62;
;                     if (kb > 0) { c62 = *(const PG8_LAS f32x4*)(exch + (((kb - 1) * 2 + 0) * 256 + bj * HALF + 32 * wc + 8 * fq + 4 * n)); c63 = *(const PG8_LAS f32x4*)(exch + (((kb - 1) * 2 + 1) * 256 + bj * HALF + 32 * wc + 8 * fq + 4 * n)); }
; #pragma unroll
;                     for (int m = 3; m >= 0; --m) { f32x4 cur = acc[ai][bj][m][n], res;
; #pragma unroll
;                         for (int j = 0; j < 4; ++j) { const float c = cur[j]; const float pv = (m > 0) ? acc[ai][bj][m > 0 ? m - 1 : 0][n][j] : (fr == 15 ? c63[j] : c62[j]); float t1, t2;
;                             asm volatile("s_nop 1\n\tv_mov_b32_dpp %0, %3 row_ror:1 row_mask:0xf bank_mask:0xf\n\tv_mov_b32_dpp %1, %3 row_ror:2 row_mask:0xf bank_mask:0xf\n\t"
;                                          "v_mov_b32_dpp %0, %2 row_shr:1 row_mask:0xf bank_mask:0xf\n\tv_mov_b32_dpp %1, %2 row_shr:2 row_mask:0xf bank_mask:0xf"
;                                          : "=&v"(t1), "=&v"(t2) : "v"(c), "v"(pv));
;                             res[j] = bb[j] + w0[j] * t2 + w1[j] * t1 + w2[j] * c; }
;                         asm volatile("" : "+v"(res[0]), "+v"(res[1]), "+v"(res[2]), "+v"(res[3]));
;                         acc[ai][bj][m][n] = res; } }
.LBB0_1188:
	v_pk_mul_f32 v[46:47], v[46:47], v[188:189] op_sel_hi:[1,0]
	v_pk_mul_f32 v[48:49], v[48:49], v[188:189] op_sel_hi:[1,0]
	v_pk_mul_f32 v[90:91], v[90:91], v[190:191] op_sel_hi:[1,0]
	v_mov_b32_e32 v139, v30
	v_fmac_f32_dpp v139, v126, v134 row_shr:2 row_mask:0xf bank_mask:0xf
	v_fmac_f32_dpp v139, v46, v134 row_shl:14 row_mask:0xf bank_mask:0xf
	v_fmac_f32_dpp v139, v126, v118 row_shr:1 row_mask:0xf bank_mask:0xf
	v_fmac_f32_dpp v139, v46, v118 row_shl:15 row_mask:0xf bank_mask:0xf
	v_fmac_f32_e32 v139, v126, v130
	v_mov_b32_e32 v141, v31
	v_fmac_f32_dpp v141, v127, v135 row_shr:2 row_mask:0xf bank_mask:0xf
	v_fmac_f32_dpp v141, v47, v135 row_shl:14 row_mask:0xf bank_mask:0xf
	v_fmac_f32_dpp v141, v127, v119 row_shr:1 row_mask:0xf bank_mask:0xf
	v_fmac_f32_dpp v141, v47, v119 row_shl:15 row_mask:0xf bank_mask:0xf
	v_fmac_f32_e32 v141, v127, v131
	v_mov_b32_e32 v138, v32
	v_fmac_f32_dpp v138, v128, v136 row_shr:2 row_mask:0xf bank_mask:0xf
	v_fmac_f32_dpp v138, v48, v136 row_shl:14 row_mask:0xf bank_mask:0xf
	v_fmac_f32_dpp v138, v128, v120 row_shr:1 row_mask:0xf bank_mask:0xf
	v_fmac_f32_dpp v138, v48, v120 row_shl:15 row_mask:0xf bank_mask:0xf
	v_fmac_f32_e32 v138, v128, v132
	v_mov_b32_e32 v140, v33
	v_fmac_f32_dpp v140, v129, v137 row_shr:2 row_mask:0xf bank_mask:0xf
	v_fmac_f32_dpp v140, v49, v137 row_shl:14 row_mask:0xf bank_mask:0xf
	v_fmac_f32_dpp v140, v129, v121 row_shr:1 row_mask:0xf bank_mask:0xf
	v_fmac_f32_dpp v140, v49, v121 row_shl:15 row_mask:0xf bank_mask:0xf
	v_fmac_f32_e32 v140, v129, v133
	v_pk_mul_f32 v[92:93], v[92:93], v[190:191] op_sel_hi:[1,0]
	v_mov_b32_e32 v147, v30
	v_fmac_f32_dpp v147, v46, v134 row_shr:2 row_mask:0xf bank_mask:0xf
	v_fmac_f32_dpp v147, v90, v134 row_shl:14 row_mask:0xf bank_mask:0xf
	v_fmac_f32_dpp v147, v46, v118 row_shr:1 row_mask:0xf bank_mask:0xf
	v_fmac_f32_dpp v147, v90, v118 row_shl:15 row_mask:0xf bank_mask:0xf
	v_fmac_f32_e32 v147, v46, v130
	v_pk_mul_f32 v[94:95], v[94:95], v[192:193] op_sel_hi:[1,0]
	v_mov_b32_e32 v149, v31
	v_fmac_f32_dpp v149, v47, v135 row_shr:2 row_mask:0xf bank_mask:0xf
	v_fmac_f32_dpp v149, v91, v135 row_shl:14 row_mask:0xf bank_mask:0xf
	v_fmac_f32_dpp v149, v47, v119 row_shr:1 row_mask:0xf bank_mask:0xf
	v_fmac_f32_dpp v149, v91, v119 row_shl:15 row_mask:0xf bank_mask:0xf
	v_fmac_f32_e32 v149, v47, v131
	v_pk_mul_f32 v[96:97], v[96:97], v[192:193] op_sel_hi:[1,0]
	v_mov_b32_e32 v146, v32
	v_fmac_f32_dpp v146, v48, v136 row_shr:2 row_mask:0xf bank_mask:0xf
	v_fmac_f32_dpp v146, v92, v136 row_shl:14 row_mask:0xf bank_mask:0xf
	v_fmac_f32_dpp v146, v48, v120 row_shr:1 row_mask:0xf bank_mask:0xf
	v_fmac_f32_dpp v146, v92, v120 row_shl:15 row_mask:0xf bank_mask:0xf
	v_fmac_f32_e32 v146, v48, v132
	v_mov_b32_e32 v148, v33
	v_fmac_f32_dpp v148, v49, v137 row_shr:2 row_mask:0xf bank_mask:0xf
	v_fmac_f32_dpp v148, v93, v137 row_shl:14 row_mask:0xf bank_mask:0xf
	v_fmac_f32_dpp v148, v49, v121 row_shr:1 row_mask:0xf bank_mask:0xf
	v_fmac_f32_dpp v148, v93, v121 row_shl:15 row_mask:0xf bank_mask:0xf
	v_fmac_f32_e32 v148, v49, v133
	s_waitcnt lgkmcnt(0)
	v_cndmask_b32_e64 v49, v142, v102, s[8:9]
	v_mov_b32_e32 v151, v30
	v_fmac_f32_dpp v151, v90, v134 row_shr:2 row_mask:0xf bank_mask:0xf
	v_fmac_f32_dpp v151, v94, v134 row_shl:14 row_mask:0xf bank_mask:0xf
	v_fmac_f32_dpp v151, v90, v118 row_shr:1 row_mask:0xf bank_mask:0xf
	v_fmac_f32_dpp v151, v94, v118 row_shl:15 row_mask:0xf bank_mask:0xf
	v_fmac_f32_e32 v151, v90, v130
	v_mov_b32_e32 v215, v31
	v_fmac_f32_dpp v215, v91, v135 row_shr:2 row_mask:0xf bank_mask:0xf
	v_fmac_f32_dpp v215, v95, v135 row_shl:14 row_mask:0xf bank_mask:0xf
	v_fmac_f32_dpp v215, v91, v119 row_shr:1 row_mask:0xf bank_mask:0xf
	v_fmac_f32_dpp v215, v95, v119 row_shl:15 row_mask:0xf bank_mask:0xf
	v_fmac_f32_e32 v215, v91, v131
	v_mov_b32_e32 v150, v32
	v_fmac_f32_dpp v150, v92, v136 row_shr:2 row_mask:0xf bank_mask:0xf
	v_fmac_f32_dpp v150, v96, v136 row_shl:14 row_mask:0xf bank_mask:0xf
	v_fmac_f32_dpp v150, v92, v120 row_shr:1 row_mask:0xf bank_mask:0xf
	v_fmac_f32_dpp v150, v96, v120 row_shl:15 row_mask:0xf bank_mask:0xf
	v_fmac_f32_e32 v150, v92, v132
	v_mov_b32_e32 v155, v33
	v_fmac_f32_dpp v155, v93, v137 row_shr:2 row_mask:0xf bank_mask:0xf
	v_fmac_f32_dpp v155, v97, v137 row_shl:14 row_mask:0xf bank_mask:0xf
	v_fmac_f32_dpp v155, v93, v121 row_shr:1 row_mask:0xf bank_mask:0xf
	v_fmac_f32_dpp v155, v97, v121 row_shl:15 row_mask:0xf bank_mask:0xf
	v_fmac_f32_e32 v155, v93, v133
	s_nop 1
	v_mov_b32_dpp v90, v49 row_ror:1 row_mask:0xf bank_mask:0xf
	v_mov_b32_dpp v91, v49 row_ror:2 row_mask:0xf bank_mask:0xf
	v_mov_b32_dpp v90, v94 row_shr:1 row_mask:0xf bank_mask:0xf
	v_mov_b32_dpp v91, v94 row_shr:2 row_mask:0xf bank_mask:0xf
	v_cndmask_b32_e64 v48, v143, v103, s[8:9]
	v_fma_f32 v134, v134, v91, v30
	v_fmac_f32_e32 v134, v118, v90
	v_fmac_f32_e32 v134, v94, v130
	v_cndmask_b32_e64 v47, v144, v104, s[8:9]
	v_mov_b32_e32 v130, v31
	v_fmac_f32_dpp v130, v95, v135 row_shr:2 row_mask:0xf bank_mask:0xf
	v_fmac_f32_dpp v130, v48, v135 row_shl:14 row_mask:0xf bank_mask:0xf
	v_fmac_f32_dpp v130, v95, v119 row_shr:1 row_mask:0xf bank_mask:0xf
	v_fmac_f32_dpp v130, v48, v119 row_shl:15 row_mask:0xf bank_mask:0xf
	s_nop 1
	v_mov_b32_dpp v30, v47 row_ror:1 row_mask:0xf bank_mask:0xf
	v_mov_b32_dpp v31, v47 row_ror:2 row_mask:0xf bank_mask:0xf
	v_mov_b32_dpp v30, v96 row_shr:1 row_mask:0xf bank_mask:0xf
	v_mov_b32_dpp v31, v96 row_shr:2 row_mask:0xf bank_mask:0xf
	v_cndmask_b32_e64 v46, v145, v105, s[8:9]
	v_fma_f32 v32, v136, v31, v32
	v_fmac_f32_e32 v32, v120, v30
	s_nop 1
	v_mov_b32_dpp v30, v46 row_ror:1 row_mask:0xf bank_mask:0xf
	v_mov_b32_dpp v31, v46 row_ror:2 row_mask:0xf bank_mask:0xf
	v_mov_b32_dpp v30, v97 row_shr:1 row_mask:0xf bank_mask:0xf
	v_mov_b32_dpp v31, v97 row_shr:2 row_mask:0xf bank_mask:0xf
	v_fmac_f32_e32 v130, v95, v131
	v_fmac_f32_e32 v33, v137, v31
	v_fmac_f32_e32 v33, v121, v30
	v_or_b32_e32 v30, 4, v186
	v_ashrrev_i32_e32 v31, 31, v30
	v_fmac_f32_e32 v32, v96, v132
	v_fmac_f32_e32 v33, v97, v133
	v_lshlrev_b64 v[30:31], 2, v[30:31]
	v_lshl_add_u64 v[46:47], s[20:21], 0, v[30:31]
	v_lshl_add_u64 v[30:31], s[22:23], 0, v[30:31]
	s_nop 0
	v_mov_b32_e32 v106, 0
	s_and_b64 vcc, exec, s[10:11]
	v_mov_b32_e32 v118, 0
	v_mov_b32_e32 v119, 0
	v_mov_b32_e32 v120, 0
	v_mov_b32_e32 v121, 0
	v_mov_b32_e32 v126, 0
	v_mov_b32_e32 v127, 0
	v_mov_b32_e32 v128, 0
	v_mov_b32_e32 v129, 0
	s_cbranch_vccnz .LBB0_1190
	v_add_u32_e32 v31, 0xfffff810, v227
	v_add_u32_e32 v30, 0xfffffc10, v227
	ds_read_b128 v[118:121], v31
	ds_read_b128 v[126:129], v30
; #define PG8_LAS __attribute__((address_space(3)))
;     __device__ __forceinline__ void operator()(f32x4 (&acc)[2][2][4][2], const Unit& u, int ui, int wr, int wc, int fr_, int fq_) const {
;     ...
;             for (int n = 0; n < 2; ++n) { const int ch = bj * 2816 + fbase + 4 * n;
;                 const f32x4 w0 = *(const f32x4*)(cw + ch), w1 = *(const f32x4*)(cw + 5632 + ch), w2 = *(const f32x4*)(cw + 2 * 5632 + ch), bb = *(const f32x4*)(cb + ch);
; #pragma unroll
;                 for (int ai = 0; ai < 2; ++ai) { const int kb = 2 * ai + wr;
;                     f32x4 c62 = (f32x4){0.f, 0.f, 0.f, 0.f}, c63 = c62;
;                     if (kb > 0) { c62 = *(const PG8_LAS f32x4*)(exch + (((kb - 1) * 2 + 0) * 256 + bj * HALF + 32 * wc + 8 * fq + 4 * n)); c63 = *(const PG8_LAS f32x4*)(exch + (((kb - 1) * 2 + 1) * 256 + bj * HALF + 32 * wc + 8 * fq + 4 * n)); }
; #pragma unroll
;                     for (int m = 3; m >= 0; --m) { f32x4 cur = acc[ai][bj][m][n], res;
; #pragma unroll
;                         for (int j = 0; j < 4; ++j) { const float c = cur[j]; const float pv = (m > 0) ? acc[ai][bj][m > 0 ? m - 1 : 0][n][j] : (fr == 15 ? c63[j] : c62[j]); float t1, t2;
;                             asm volatile("s_nop 1\n\tv_mov_b32_dpp %0, %3 row_ror:1 row_mask:0xf bank_mask:0xf\n\tv_mov_b32_dpp %1, %3 row_ror:2 row_mask:0xf bank_mask:0xf\n\t"
;                                          "v_mov_b32_dpp %0, %2 row_shr:1 row_mask:0xf bank_mask:0xf\n\tv_mov_b32_dpp %1, %2 row_shr:2 row_mask:0xf bank_mask:0xf"
;                                          : "=&v"(t1), "=&v"(t2) : "v"(c), "v"(pv));
;                             res[j] = bb[j] + w0[j] * t2 + w1[j] * t1 + w2[j] * c; }
;                         asm volatile("" : "+v"(res[0]), "+v"(res[1]), "+v"(res[2]), "+v"(res[3]));
;                         acc[ai][bj][m][n] = res; } }
.LBB0_1190:
	v_mov_b32_e32 v30, v194
	v_mov_b32_e32 v31, v194
	v_mov_b32_e32 v197, v196
	v_pk_mul_f32 v[30:31], v[80:81], v[30:31]
	v_mov_b32_e32 v80, v196
	v_mov_b32_e32 v81, v196
	v_pk_mul_f32 v[76:77], v[76:77], v[80:81]
	v_pk_mul_f32 v[74:75], v[74:75], v[196:197]
	v_mov_b32_e32 v195, v194
	v_pk_mul_f32 v[78:79], v[78:79], v[194:195]
	s_waitcnt vmcnt(0)
	v_mov_b32_e32 v133, v248
	v_fmac_f32_dpp v133, v110, v234 row_shr:2 row_mask:0xf bank_mask:0xf
	v_fmac_f32_dpp v133, v74, v234 row_shl:14 row_mask:0xf bank_mask:0xf
	v_fmac_f32_dpp v133, v110, v240 row_shr:1 row_mask:0xf bank_mask:0xf
	v_fmac_f32_dpp v133, v74, v240 row_shl:15 row_mask:0xf bank_mask:0xf
	v_fmac_f32_e32 v133, v110, v244
	v_mov_b32_e32 v131, v249
	v_fmac_f32_dpp v131, v111, v235 row_shr:2 row_mask:0xf bank_mask:0xf
	v_fmac_f32_dpp v131, v75, v235 row_shl:14 row_mask:0xf bank_mask:0xf
	v_fmac_f32_dpp v131, v111, v241 row_shr:1 row_mask:0xf bank_mask:0xf
	v_fmac_f32_dpp v131, v75, v241 row_shl:15 row_mask:0xf bank_mask:0xf
	v_fmac_f32_e32 v131, v111, v245
	v_mov_b32_e32 v132, v250
	v_fmac_f32_dpp v132, v112, v236 row_shr:2 row_mask:0xf bank_mask:0xf
	v_fmac_f32_dpp v132, v76, v236 row_shl:14 row_mask:0xf bank_mask:0xf
	v_fmac_f32_dpp v132, v112, v242 row_shr:1 row_mask:0xf bank_mask:0xf
	v_fmac_f32_dpp v132, v76, v242 row_shl:15 row_mask:0xf bank_mask:0xf
	v_fmac_f32_e32 v132, v112, v246
	v_mov_b32_e32 v135, v251
	v_fmac_f32_dpp v135, v113, v237 row_shr:2 row_mask:0xf bank_mask:0xf
	v_fmac_f32_dpp v135, v77, v237 row_shl:14 row_mask:0xf bank_mask:0xf
	v_fmac_f32_dpp v135, v113, v243 row_shr:1 row_mask:0xf bank_mask:0xf
	v_fmac_f32_dpp v135, v77, v243 row_shl:15 row_mask:0xf bank_mask:0xf
	v_fmac_f32_e32 v135, v113, v247
	s_and_b64 vcc, exec, s[12:13]
	v_mov_b32_e32 v142, v248
	v_fmac_f32_dpp v142, v74, v234 row_shr:2 row_mask:0xf bank_mask:0xf
	v_fmac_f32_dpp v142, v78, v234 row_shl:14 row_mask:0xf bank_mask:0xf
	v_fmac_f32_dpp v142, v74, v240 row_shr:1 row_mask:0xf bank_mask:0xf
	v_fmac_f32_dpp v142, v78, v240 row_shl:15 row_mask:0xf bank_mask:0xf
	v_fmac_f32_e32 v142, v74, v244
	v_mov_b32_e32 v107, 0
	v_mov_b32_e32 v136, v249
	v_fmac_f32_dpp v136, v75, v235 row_shr:2 row_mask:0xf bank_mask:0xf
	v_fmac_f32_dpp v136, v79, v235 row_shl:14 row_mask:0xf bank_mask:0xf
	v_fmac_f32_dpp v136, v75, v241 row_shr:1 row_mask:0xf bank_mask:0xf
	v_fmac_f32_dpp v136, v79, v241 row_shl:15 row_mask:0xf bank_mask:0xf
	v_fmac_f32_e32 v136, v75, v245
	v_mov_b32_e32 v108, 0
	v_mov_b32_e32 v137, v250
	v_fmac_f32_dpp v137, v76, v236 row_shr:2 row_mask:0xf bank_mask:0xf
	v_fmac_f32_dpp v137, v30, v236 row_shl:14 row_mask:0xf bank_mask:0xf
	v_fmac_f32_dpp v137, v76, v242 row_shr:1 row_mask:0xf bank_mask:0xf
	v_fmac_f32_dpp v137, v30, v242 row_shl:15 row_mask:0xf bank_mask:0xf
	v_fmac_f32_e32 v137, v76, v246
	v_mov_b32_e32 v143, v251
	v_fmac_f32_dpp v143, v77, v237 row_shr:2 row_mask:0xf bank_mask:0xf
	v_fmac_f32_dpp v143, v31, v237 row_shl:14 row_mask:0xf bank_mask:0xf
	v_fmac_f32_dpp v143, v77, v243 row_shr:1 row_mask:0xf bank_mask:0xf
	v_fmac_f32_dpp v143, v31, v243 row_shl:15 row_mask:0xf bank_mask:0xf
	v_fmac_f32_e32 v143, v77, v247
	v_mov_b32_e32 v109, 0
	v_mov_b32_e32 v225, v248
	v_fmac_f32_dpp v225, v78, v234 row_shr:2 row_mask:0xf bank_mask:0xf
	v_fmac_f32_dpp v225, v122, v234 row_shl:14 row_mask:0xf bank_mask:0xf
	v_fmac_f32_dpp v225, v78, v240 row_shr:1 row_mask:0xf bank_mask:0xf
	v_fmac_f32_dpp v225, v122, v240 row_shl:15 row_mask:0xf bank_mask:0xf
	v_fmac_f32_e32 v225, v78, v244
	v_mov_b32_e32 v144, v249
	v_fmac_f32_dpp v144, v79, v235 row_shr:2 row_mask:0xf bank_mask:0xf
	v_fmac_f32_dpp v144, v123, v235 row_shl:14 row_mask:0xf bank_mask:0xf
	v_fmac_f32_dpp v144, v79, v241 row_shr:1 row_mask:0xf bank_mask:0xf
	v_fmac_f32_dpp v144, v123, v241 row_shl:15 row_mask:0xf bank_mask:0xf
	v_fmac_f32_e32 v144, v79, v245
	v_mov_b32_e32 v145, v250
	v_fmac_f32_dpp v145, v30, v236 row_shr:2 row_mask:0xf bank_mask:0xf
	v_fmac_f32_dpp v145, v124, v236 row_shl:14 row_mask:0xf bank_mask:0xf
	v_fmac_f32_dpp v145, v30, v242 row_shr:1 row_mask:0xf bank_mask:0xf
	v_fmac_f32_dpp v145, v124, v242 row_shl:15 row_mask:0xf bank_mask:0xf
	v_fmac_f32_e32 v145, v30, v246
	s_waitcnt lgkmcnt(0)
	v_cndmask_b32_e64 v75, v118, v126, s[8:9]
	v_mov_b32_e32 v226, v251
	v_fmac_f32_dpp v226, v31, v237 row_shr:2 row_mask:0xf bank_mask:0xf
	v_fmac_f32_dpp v226, v125, v237 row_shl:14 row_mask:0xf bank_mask:0xf
	v_fmac_f32_dpp v226, v31, v243 row_shr:1 row_mask:0xf bank_mask:0xf
	v_fmac_f32_dpp v226, v125, v243 row_shl:15 row_mask:0xf bank_mask:0xf
	v_fmac_f32_e32 v226, v31, v247
	v_cndmask_b32_e64 v74, v119, v127, s[8:9]
	v_mov_b32_e32 v126, v248
	v_fmac_f32_dpp v126, v122, v234 row_shr:2 row_mask:0xf bank_mask:0xf
	v_fmac_f32_dpp v126, v75, v234 row_shl:14 row_mask:0xf bank_mask:0xf
	v_fmac_f32_dpp v126, v122, v240 row_shr:1 row_mask:0xf bank_mask:0xf
	v_fmac_f32_dpp v126, v75, v240 row_shl:15 row_mask:0xf bank_mask:0xf
	v_fmac_f32_e32 v126, v122, v244
	v_cndmask_b32_e64 v31, v120, v128, s[8:9]
	v_mov_b32_e32 v122, v249
	v_fmac_f32_dpp v122, v123, v235 row_shr:2 row_mask:0xf bank_mask:0xf
	v_fmac_f32_dpp v122, v74, v235 row_shl:14 row_mask:0xf bank_mask:0xf
	v_fmac_f32_dpp v122, v123, v241 row_shr:1 row_mask:0xf bank_mask:0xf
	v_fmac_f32_dpp v122, v74, v241 row_shl:15 row_mask:0xf bank_mask:0xf
	v_fmac_f32_e32 v122, v123, v245
	v_cndmask_b32_e64 v30, v121, v129, s[8:9]
	v_mov_b32_e32 v123, v250
	v_fmac_f32_dpp v123, v124, v236 row_shr:2 row_mask:0xf bank_mask:0xf
	v_fmac_f32_dpp v123, v31, v236 row_shl:14 row_mask:0xf bank_mask:0xf
	v_fmac_f32_dpp v123, v124, v242 row_shr:1 row_mask:0xf bank_mask:0xf
	v_fmac_f32_dpp v123, v31, v242 row_shl:15 row_mask:0xf bank_mask:0xf
	v_fmac_f32_e32 v123, v124, v246
	v_mov_b32_e32 v75, 0
	v_mov_b32_e32 v124, v251
	v_fmac_f32_dpp v124, v125, v237 row_shr:2 row_mask:0xf bank_mask:0xf
	v_fmac_f32_dpp v124, v30, v237 row_shl:14 row_mask:0xf bank_mask:0xf
	v_fmac_f32_dpp v124, v125, v243 row_shr:1 row_mask:0xf bank_mask:0xf
	v_fmac_f32_dpp v124, v30, v243 row_shl:15 row_mask:0xf bank_mask:0xf
	v_fmac_f32_e32 v124, v125, v247
	v_mov_b32_e32 v74, 0
	v_mov_b32_e32 v76, 0
	v_mov_b32_e32 v77, 0
	s_cbranch_vccnz .LBB0_1192
	ds_read_b128 v[106:109], v227 offset:2064
	ds_read_b128 v[74:77], v227 offset:3088
; #define PG8_LAS __attribute__((address_space(3)))
;     __device__ __forceinline__ void operator()(f32x4 (&acc)[2][2][4][2], const Unit& u, int ui, int wr, int wc, int fr_, int fq_) const {
;     ...
;             for (int n = 0; n < 2; ++n) { const int ch = bj * 2816 + fbase + 4 * n;
;                 const f32x4 w0 = *(const f32x4*)(cw + ch), w1 = *(const f32x4*)(cw + 5632 + ch), w2 = *(const f32x4*)(cw + 2 * 5632 + ch), bb = *(const f32x4*)(cb + ch);
; #pragma unroll
;                 for (int ai = 0; ai < 2; ++ai) { const int kb = 2 * ai + wr;
;                     f32x4 c62 = (f32x4){0.f, 0.f, 0.f, 0.f}, c63 = c62;
;                     if (kb > 0) { c62 = *(const PG8_LAS f32x4*)(exch + (((kb - 1) * 2 + 0) * 256 + bj * HALF + 32 * wc + 8 * fq + 4 * n)); c63 = *(const PG8_LAS f32x4*)(exch + (((kb - 1) * 2 + 1) * 256 + bj * HALF + 32 * wc + 8 * fq + 4 * n)); }
; #pragma unroll
;                     for (int m = 3; m >= 0; --m) { f32x4 cur = acc[ai][bj][m][n], res;
; #pragma unroll
;                         for (int j = 0; j < 4; ++j) { const float c = cur[j]; const float pv = (m > 0) ? acc[ai][bj][m > 0 ? m - 1 : 0][n][j] : (fr == 15 ? c63[j] : c62[j]); float t1, t2;
;                             asm volatile("s_nop 1\n\tv_mov_b32_dpp %0, %3 row_ror:1 row_mask:0xf bank_mask:0xf\n\tv_mov_b32_dpp %1, %3 row_ror:2 row_mask:0xf bank_mask:0xf\n\t"
;                                          "v_mov_b32_dpp %0, %2 row_shr:1 row_mask:0xf bank_mask:0xf\n\tv_mov_b32_dpp %1, %2 row_shr:2 row_mask:0xf bank_mask:0xf"
;                                          : "=&v"(t1), "=&v"(t2) : "v"(c), "v"(pv));
;                             res[j] = bb[j] + w0[j] * t2 + w1[j] * t1 + w2[j] * c; }
;                         asm volatile("" : "+v"(res[0]), "+v"(res[1]), "+v"(res[2]), "+v"(res[3]));
;                         acc[ai][bj][m][n] = res; } }
.LBB0_1192:
	v_mov_b32_e32 v30, v192
	v_mov_b32_e32 v31, v192
	v_pk_mul_f32 v[30:31], v[68:69], v[30:31]
	v_mov_b32_e32 v68, v190
	v_mov_b32_e32 v69, v190
	v_mov_b32_e32 v189, v188
	v_pk_mul_f32 v[64:65], v[64:65], v[68:69]
	v_mov_b32_e32 v68, v188
	v_mov_b32_e32 v69, v188
	v_pk_mul_f32 v[56:57], v[56:57], v[68:69]
	v_pk_mul_f32 v[54:55], v[54:55], v[188:189]
	v_mov_b32_e32 v191, v190
	v_pk_mul_f32 v[62:63], v[62:63], v[190:191]
	v_mov_b32_e32 v112, v248
	v_fmac_f32_dpp v112, v114, v234 row_shr:2 row_mask:0xf bank_mask:0xf
	v_fmac_f32_dpp v112, v54, v234 row_shl:14 row_mask:0xf bank_mask:0xf
	v_fmac_f32_dpp v112, v114, v240 row_shr:1 row_mask:0xf bank_mask:0xf
	v_fmac_f32_dpp v112, v54, v240 row_shl:15 row_mask:0xf bank_mask:0xf
	v_fmac_f32_e32 v112, v114, v244
	v_mov_b32_e32 v110, v249
	v_fmac_f32_dpp v110, v115, v235 row_shr:2 row_mask:0xf bank_mask:0xf
	v_fmac_f32_dpp v110, v55, v235 row_shl:14 row_mask:0xf bank_mask:0xf
	v_fmac_f32_dpp v110, v115, v241 row_shr:1 row_mask:0xf bank_mask:0xf
	v_fmac_f32_dpp v110, v55, v241 row_shl:15 row_mask:0xf bank_mask:0xf
	v_fmac_f32_e32 v110, v115, v245
	v_mov_b32_e32 v111, v250
	v_fmac_f32_dpp v111, v116, v236 row_shr:2 row_mask:0xf bank_mask:0xf
	v_fmac_f32_dpp v111, v56, v236 row_shl:14 row_mask:0xf bank_mask:0xf
	v_fmac_f32_dpp v111, v116, v242 row_shr:1 row_mask:0xf bank_mask:0xf
	v_fmac_f32_dpp v111, v56, v242 row_shl:15 row_mask:0xf bank_mask:0xf
	v_fmac_f32_e32 v111, v116, v246
	v_mov_b32_e32 v113, v251
	v_fmac_f32_dpp v113, v117, v237 row_shr:2 row_mask:0xf bank_mask:0xf
	v_fmac_f32_dpp v113, v57, v237 row_shl:14 row_mask:0xf bank_mask:0xf
	v_fmac_f32_dpp v113, v117, v243 row_shr:1 row_mask:0xf bank_mask:0xf
	v_fmac_f32_dpp v113, v57, v243 row_shl:15 row_mask:0xf bank_mask:0xf
	v_fmac_f32_e32 v113, v117, v247
	v_mov_b32_e32 v193, v192
	v_mov_b32_e32 v116, v248
	v_fmac_f32_dpp v116, v54, v234 row_shr:2 row_mask:0xf bank_mask:0xf
	v_fmac_f32_dpp v116, v62, v234 row_shl:14 row_mask:0xf bank_mask:0xf
	v_fmac_f32_dpp v116, v54, v240 row_shr:1 row_mask:0xf bank_mask:0xf
	v_fmac_f32_dpp v116, v62, v240 row_shl:15 row_mask:0xf bank_mask:0xf
	v_fmac_f32_e32 v116, v54, v244
	v_pk_mul_f32 v[66:67], v[66:67], v[192:193]
	v_mov_b32_e32 v114, v249
	v_fmac_f32_dpp v114, v55, v235 row_shr:2 row_mask:0xf bank_mask:0xf
	v_fmac_f32_dpp v114, v63, v235 row_shl:14 row_mask:0xf bank_mask:0xf
	v_fmac_f32_dpp v114, v55, v241 row_shr:1 row_mask:0xf bank_mask:0xf
	v_fmac_f32_dpp v114, v63, v241 row_shl:15 row_mask:0xf bank_mask:0xf
	v_fmac_f32_e32 v114, v55, v245
	s_movk_i32 s0, 0x2000
	v_mov_b32_e32 v115, v250
	v_fmac_f32_dpp v115, v56, v236 row_shr:2 row_mask:0xf bank_mask:0xf
	v_fmac_f32_dpp v115, v64, v236 row_shl:14 row_mask:0xf bank_mask:0xf
	v_fmac_f32_dpp v115, v56, v242 row_shr:1 row_mask:0xf bank_mask:0xf
	v_fmac_f32_dpp v115, v64, v242 row_shl:15 row_mask:0xf bank_mask:0xf
	v_fmac_f32_e32 v115, v56, v246
	v_mov_b32_e32 v117, v251
	v_fmac_f32_dpp v117, v57, v237 row_shr:2 row_mask:0xf bank_mask:0xf
	v_fmac_f32_dpp v117, v65, v237 row_shl:14 row_mask:0xf bank_mask:0xf
	v_fmac_f32_dpp v117, v57, v243 row_shr:1 row_mask:0xf bank_mask:0xf
	v_fmac_f32_dpp v117, v65, v243 row_shl:15 row_mask:0xf bank_mask:0xf
	v_fmac_f32_e32 v117, v57, v247
	s_waitcnt lgkmcnt(0)
; #define PG8_LAS __attribute__((address_space(3)))
;     __device__ __forceinline__ void operator()(f32x4 (&acc)[2][2][4][2], const Unit& u, int ui, int wr, int wc, int fr_, int fq_) const {
;     ...
;         for (int bj = 0; bj < 2; ++bj)
; #pragma unroll
;             for (int n = 0; n < 2; ++n) { const int ch = bj * 2816 + fbase + 4 * n;
;                 const f32x4 w0 = *(const f32x4*)(cw + ch), w1 = *(const f32x4*)(cw + 5632 + ch), w2 = *(const f32x4*)(cw + 2 * 5632 + ch), bb = *(const f32x4*)(cb + ch);
; #pragma unroll
;                 for (int ai = 0; ai < 2; ++ai) { const int kb = 2 * ai + wr;
;                     f32x4 c62 = (f32x4){0.f, 0.f, 0.f, 0.f}, c63 = c62;
;                     if (kb > 0) { c62 = *(const PG8_LAS f32x4*)(exch + (((kb - 1) * 2 + 0) * 256 + bj * HALF + 32 * wc + 8 * fq + 4 * n)); c63 = *(const PG8_LAS f32x4*)(exch + (((kb - 1) * 2 + 1) * 256 + bj * HALF + 32 * wc + 8 * fq + 4 * n)); }
; #pragma unroll
;                     for (int m = 3; m >= 0; --m) { f32x4 cur = acc[ai][bj][m][n], res;
; #pragma unroll
;                         for (int j = 0; j < 4; ++j) { const float c = cur[j]; const float pv = (m > 0) ? acc[ai][bj][m > 0 ? m - 1 : 0][n][j] : (fr == 15 ? c63[j] : c62[j]); float t1, t2;
;                             asm volatile("s_nop 1\n\tv_mov_b32_dpp %0, %3 row_ror:1 row_mask:0xf bank_mask:0xf\n\tv_mov_b32_dpp %1, %3 row_ror:2 row_mask:0xf bank_mask:0xf\n\t"
;                                          "v_mov_b32_dpp %0, %2 row_shr:1 row_mask:0xf bank_mask:0xf\n\tv_mov_b32_dpp %1, %2 row_shr:2 row_mask:0xf bank_mask:0xf"
;                                          : "=&v"(t1), "=&v"(t2) : "v"(c), "v"(pv));
;                             res[j] = bb[j] + w0[j] * t2 + w1[j] * t1 + w2[j] * c; }
;                         asm volatile("" : "+v"(res[0]), "+v"(res[1]), "+v"(res[2]), "+v"(res[3]));
;                         acc[ai][bj][m][n] = res; } }
	v_cndmask_b32_e64 v57, v106, v74, s[8:9]
	v_mov_b32_e32 v120, v248
	v_fmac_f32_dpp v120, v62, v234 row_shr:2 row_mask:0xf bank_mask:0xf
	v_fmac_f32_dpp v120, v66, v234 row_shl:14 row_mask:0xf bank_mask:0xf
	v_fmac_f32_dpp v120, v62, v240 row_shr:1 row_mask:0xf bank_mask:0xf
	v_fmac_f32_dpp v120, v66, v240 row_shl:15 row_mask:0xf bank_mask:0xf
	v_fmac_f32_e32 v120, v62, v244
	v_mov_b32_e32 v118, v249
	v_fmac_f32_dpp v118, v63, v235 row_shr:2 row_mask:0xf bank_mask:0xf
	v_fmac_f32_dpp v118, v67, v235 row_shl:14 row_mask:0xf bank_mask:0xf
	v_fmac_f32_dpp v118, v63, v241 row_shr:1 row_mask:0xf bank_mask:0xf
	v_fmac_f32_dpp v118, v67, v241 row_shl:15 row_mask:0xf bank_mask:0xf
	v_fmac_f32_e32 v118, v63, v245
	v_mov_b32_e32 v119, v250
	v_fmac_f32_dpp v119, v64, v236 row_shr:2 row_mask:0xf bank_mask:0xf
	v_fmac_f32_dpp v119, v30, v236 row_shl:14 row_mask:0xf bank_mask:0xf
	v_fmac_f32_dpp v119, v64, v242 row_shr:1 row_mask:0xf bank_mask:0xf
	v_fmac_f32_dpp v119, v30, v242 row_shl:15 row_mask:0xf bank_mask:0xf
	v_fmac_f32_e32 v119, v64, v246
	v_mov_b32_e32 v121, v251
	v_fmac_f32_dpp v121, v65, v237 row_shr:2 row_mask:0xf bank_mask:0xf
	v_fmac_f32_dpp v121, v31, v237 row_shl:14 row_mask:0xf bank_mask:0xf
	v_fmac_f32_dpp v121, v65, v243 row_shr:1 row_mask:0xf bank_mask:0xf
	v_fmac_f32_dpp v121, v31, v243 row_shl:15 row_mask:0xf bank_mask:0xf
	v_fmac_f32_e32 v121, v65, v247
	v_cndmask_b32_e64 v56, v107, v75, s[8:9]
	v_mov_b32_e32 v106, v248
	v_fmac_f32_dpp v106, v66, v234 row_shr:2 row_mask:0xf bank_mask:0xf
	v_fmac_f32_dpp v106, v57, v234 row_shl:14 row_mask:0xf bank_mask:0xf
	v_fmac_f32_dpp v106, v66, v240 row_shr:1 row_mask:0xf bank_mask:0xf
	v_fmac_f32_dpp v106, v57, v240 row_shl:15 row_mask:0xf bank_mask:0xf
	v_cndmask_b32_e64 v55, v108, v76, s[8:9]
	v_mov_b32_e32 v102, v249
	v_fmac_f32_dpp v102, v67, v235 row_shr:2 row_mask:0xf bank_mask:0xf
	v_fmac_f32_dpp v102, v56, v235 row_shl:14 row_mask:0xf bank_mask:0xf
	v_fmac_f32_dpp v102, v67, v241 row_shr:1 row_mask:0xf bank_mask:0xf
	v_fmac_f32_dpp v102, v56, v241 row_shl:15 row_mask:0xf bank_mask:0xf
	s_nop 1
	v_mov_b32_dpp v46, v55 row_ror:1 row_mask:0xf bank_mask:0xf
	v_mov_b32_dpp v47, v55 row_ror:2 row_mask:0xf bank_mask:0xf
	v_mov_b32_dpp v46, v30 row_shr:1 row_mask:0xf bank_mask:0xf
	v_mov_b32_dpp v47, v30 row_shr:2 row_mask:0xf bank_mask:0xf
	v_cndmask_b32_e64 v54, v109, v77, s[8:9]
	v_mov_b32_e32 v48, v250
	v_fma_f32 v48, v236, v47, v48
	v_fmac_f32_e32 v48, v242, v46
	v_fmac_f32_e32 v48, v30, v246
	s_nop 1
	v_mov_b32_dpp v30, v54 row_ror:1 row_mask:0xf bank_mask:0xf
	v_mov_b32_dpp v46, v54 row_ror:2 row_mask:0xf bank_mask:0xf
	v_mov_b32_dpp v30, v31 row_shr:1 row_mask:0xf bank_mask:0xf
	v_mov_b32_dpp v46, v31 row_shr:2 row_mask:0xf bank_mask:0xf
	v_fmac_f32_e32 v106, v66, v244
	v_mov_b32_e32 v49, v251
	v_fmac_f32_e32 v49, v237, v46
	v_fmac_f32_e32 v49, v243, v30
	v_add_co_u32_e32 v30, vcc, s0, v204
	v_fmac_f32_e32 v49, v31, v247
	s_nop 0
	v_addc_co_u32_e32 v31, vcc, 0, v205, vcc
	v_add_co_u32_e32 v46, vcc, s0, v202
	v_fmac_f32_e32 v102, v67, v245
	s_nop 0
	v_addc_co_u32_e32 v47, vcc, 0, v203, vcc
	v_add_co_u32_e32 v54, vcc, 0x2000, v200
	global_load_dwordx4 v[62:65], v[30:31], off offset:3072
	global_load_dwordx4 v[66:69], v[46:47], off offset:3072
	global_load_dwordx4 v[234:237], v[30:31], off offset:3088
	global_load_dwordx4 v[240:243], v[46:47], off offset:3088
	v_addc_co_u32_e32 v55, vcc, 0, v201, vcc
	global_load_dwordx4 v[74:77], v[54:55], off offset:3072
	global_load_dwordx4 v[244:247], v[54:55], off offset:3088
	v_add_co_u32_e32 v54, vcc, 0x2000, v198
	v_mov_b32_e32 v78, 0
	s_nop 0
	v_addc_co_u32_e32 v55, vcc, 0, v199, vcc
	global_load_dwordx4 v[248:251], v[54:55], off offset:3088
	global_load_dwordx4 v[54:57], v[54:55], off offset:3072
	s_and_b64 vcc, exec, s[10:11]
	v_mov_b32_e32 v90, 0
	v_mov_b32_e32 v91, 0
	v_mov_b32_e32 v92, 0
	v_mov_b32_e32 v93, 0
	v_mov_b32_e32 v94, 0
	v_mov_b32_e32 v95, 0
	v_mov_b32_e32 v96, 0
	v_mov_b32_e32 v97, 0
	s_cbranch_vccnz .LBB0_1194
	v_add_u32_e32 v80, s43, v228
	v_add_u32_e32 v79, s30, v228
	ds_read_b128 v[90:93], v80
	ds_read_b128 v[94:97], v79

; #define PG8_LAS __attribute__((address_space(3)))
;     __device__ __forceinline__ void operator()(f32x4 (&acc)[2][2][4][2], const Unit& u, int ui, int wr, int wc, int fr_, int fq_) const {
;     ...
;         for (int bj = 0; bj < 2; ++bj)
; #pragma unroll
;             for (int n = 0; n < 2; ++n) { const int ch = bj * 2816 + fbase + 4 * n;
;                 const f32x4 w0 = *(const f32x4*)(cw + ch), w1 = *(const f32x4*)(cw + 5632 + ch), w2 = *(const f32x4*)(cw + 2 * 5632 + ch), bb = *(const f32x4*)(cb + ch);
; #pragma unroll
;                 for (int ai = 0; ai < 2; ++ai) { const int kb = 2 * ai + wr;
;                     f32x4 c62 = (f32x4){0.f, 0.f, 0.f, 0.f}, c63 = c62;
;                     if (kb > 0) { c62 = *(const PG8_LAS f32x4*)(exch + (((kb - 1) * 2 + 0) * 256 + bj * HALF + 32 * wc + 8 * fq + 4 * n)); c63 = *(const PG8_LAS f32x4*)(exch + (((kb - 1) * 2 + 1) * 256 + bj * HALF + 32 * wc + 8 * fq + 4 * n)); }
; #pragma unroll
;                     for (int m = 3; m >= 0; --m) { f32x4 cur = acc[ai][bj][m][n], res;
; #pragma unroll
;                         for (int j = 0; j < 4; ++j) { const float c = cur[j]; const float pv = (m > 0) ? acc[ai][bj][m > 0 ? m - 1 : 0][n][j] : (fr == 15 ? c63[j] : c62[j]); float t1, t2;
;                             asm volatile("s_nop 1\n\tv_mov_b32_dpp %0, %3 row_ror:1 row_mask:0xf bank_mask:0xf\n\tv_mov_b32_dpp %1, %3 row_ror:2 row_mask:0xf bank_mask:0xf\n\t"
;                                          "v_mov_b32_dpp %0, %2 row_shr:1 row_mask:0xf bank_mask:0xf\n\tv_mov_b32_dpp %1, %2 row_shr:2 row_mask:0xf bank_mask:0xf"
;                                          : "=&v"(t1), "=&v"(t2) : "v"(c), "v"(pv));
;                             res[j] = bb[j] + w0[j] * t2 + w1[j] * t1 + w2[j] * c; }
;                         asm volatile("" : "+v"(res[0]), "+v"(res[1]), "+v"(res[2]), "+v"(res[3]));
;                         acc[ai][bj][m][n] = res; } }
.LBB0_1196:
	v_mov_b32_e32 v42, v192
	v_mov_b32_e32 v43, v192
	v_pk_mul_f32 v[36:37], v[36:37], v[42:43]
	v_mov_b32_e32 v42, v190
	v_mov_b32_e32 v43, v190
	v_pk_mul_f32 v[28:29], v[28:29], v[42:43]
	v_mov_b32_e32 v42, v188
	v_mov_b32_e32 v43, v188
	v_pk_mul_f32 v[24:25], v[24:25], v[42:43]
	v_pk_mul_f32 v[22:23], v[22:23], v[188:189]
	v_pk_mul_f32 v[26:27], v[26:27], v[190:191]
	v_pk_mul_f32 v[34:35], v[34:35], v[192:193]
	v_mov_b32_e32 v87, v54
	v_fmac_f32_dpp v87, v82, v62 row_shr:2 row_mask:0xf bank_mask:0xf
	v_fmac_f32_dpp v87, v22, v62 row_shl:14 row_mask:0xf bank_mask:0xf
	v_fmac_f32_dpp v87, v82, v66 row_shr:1 row_mask:0xf bank_mask:0xf
	v_fmac_f32_dpp v87, v22, v66 row_shl:15 row_mask:0xf bank_mask:0xf
	v_fmac_f32_e32 v87, v82, v74
	v_mov_b32_e32 v86, v55
	v_fmac_f32_dpp v86, v83, v63 row_shr:2 row_mask:0xf bank_mask:0xf
	v_fmac_f32_dpp v86, v23, v63 row_shl:14 row_mask:0xf bank_mask:0xf
	v_fmac_f32_dpp v86, v83, v67 row_shr:1 row_mask:0xf bank_mask:0xf
	v_fmac_f32_dpp v86, v23, v67 row_shl:15 row_mask:0xf bank_mask:0xf
	v_fmac_f32_e32 v86, v83, v75
	v_mov_b32_e32 v82, v56
	v_fmac_f32_dpp v82, v84, v64 row_shr:2 row_mask:0xf bank_mask:0xf
	v_fmac_f32_dpp v82, v24, v64 row_shl:14 row_mask:0xf bank_mask:0xf
	v_fmac_f32_dpp v82, v84, v68 row_shr:1 row_mask:0xf bank_mask:0xf
	v_fmac_f32_dpp v82, v24, v68 row_shl:15 row_mask:0xf bank_mask:0xf
	v_fmac_f32_e32 v82, v84, v76
	v_mov_b32_e32 v83, v57
	v_fmac_f32_dpp v83, v85, v65 row_shr:2 row_mask:0xf bank_mask:0xf
	v_fmac_f32_dpp v83, v25, v65 row_shl:14 row_mask:0xf bank_mask:0xf
	v_fmac_f32_dpp v83, v85, v69 row_shr:1 row_mask:0xf bank_mask:0xf
	v_fmac_f32_dpp v83, v25, v69 row_shl:15 row_mask:0xf bank_mask:0xf
	v_fmac_f32_e32 v83, v85, v77
	v_mov_b32_e32 v44, 0
	v_mov_b32_e32 v89, v54
	v_fmac_f32_dpp v89, v22, v62 row_shr:2 row_mask:0xf bank_mask:0xf
	v_fmac_f32_dpp v89, v26, v62 row_shl:14 row_mask:0xf bank_mask:0xf
	v_fmac_f32_dpp v89, v22, v66 row_shr:1 row_mask:0xf bank_mask:0xf
	v_fmac_f32_dpp v89, v26, v66 row_shl:15 row_mask:0xf bank_mask:0xf
	v_fmac_f32_e32 v89, v22, v74
	v_mov_b32_e32 v45, 0
	v_mov_b32_e32 v88, v55
	v_fmac_f32_dpp v88, v23, v63 row_shr:2 row_mask:0xf bank_mask:0xf
	v_fmac_f32_dpp v88, v27, v63 row_shl:14 row_mask:0xf bank_mask:0xf
	v_fmac_f32_dpp v88, v23, v67 row_shr:1 row_mask:0xf bank_mask:0xf
	v_fmac_f32_dpp v88, v27, v67 row_shl:15 row_mask:0xf bank_mask:0xf
	v_fmac_f32_e32 v88, v23, v75
	v_mov_b32_e32 v42, 0
	v_mov_b32_e32 v84, v56
	v_fmac_f32_dpp v84, v24, v64 row_shr:2 row_mask:0xf bank_mask:0xf
	v_fmac_f32_dpp v84, v28, v64 row_shl:14 row_mask:0xf bank_mask:0xf
	v_fmac_f32_dpp v84, v24, v68 row_shr:1 row_mask:0xf bank_mask:0xf
	v_fmac_f32_dpp v84, v28, v68 row_shl:15 row_mask:0xf bank_mask:0xf
	v_fmac_f32_e32 v84, v24, v76
	v_mov_b32_e32 v85, v57
	v_fmac_f32_dpp v85, v25, v65 row_shr:2 row_mask:0xf bank_mask:0xf
	v_fmac_f32_dpp v85, v29, v65 row_shl:14 row_mask:0xf bank_mask:0xf
	v_fmac_f32_dpp v85, v25, v69 row_shr:1 row_mask:0xf bank_mask:0xf
	v_fmac_f32_dpp v85, v29, v69 row_shl:15 row_mask:0xf bank_mask:0xf
	v_fmac_f32_e32 v85, v25, v77
	s_waitcnt lgkmcnt(0)
	v_cndmask_b32_e64 v25, v78, v38, s[8:9]
	v_mov_b32_e32 v93, v54
	v_fmac_f32_dpp v93, v26, v62 row_shr:2 row_mask:0xf bank_mask:0xf
	v_fmac_f32_dpp v93, v34, v62 row_shl:14 row_mask:0xf bank_mask:0xf
	v_fmac_f32_dpp v93, v26, v66 row_shr:1 row_mask:0xf bank_mask:0xf
	v_fmac_f32_dpp v93, v34, v66 row_shl:15 row_mask:0xf bank_mask:0xf
	v_fmac_f32_e32 v93, v26, v74
	v_mov_b32_e32 v92, v55
	v_fmac_f32_dpp v92, v27, v63 row_shr:2 row_mask:0xf bank_mask:0xf
	v_fmac_f32_dpp v92, v35, v63 row_shl:14 row_mask:0xf bank_mask:0xf
	v_fmac_f32_dpp v92, v27, v67 row_shr:1 row_mask:0xf bank_mask:0xf
	v_fmac_f32_dpp v92, v35, v67 row_shl:15 row_mask:0xf bank_mask:0xf
	v_fmac_f32_e32 v92, v27, v75
	v_mov_b32_e32 v90, v56
	v_fmac_f32_dpp v90, v28, v64 row_shr:2 row_mask:0xf bank_mask:0xf
	v_fmac_f32_dpp v90, v36, v64 row_shl:14 row_mask:0xf bank_mask:0xf
	v_fmac_f32_dpp v90, v28, v68 row_shr:1 row_mask:0xf bank_mask:0xf
	v_fmac_f32_dpp v90, v36, v68 row_shl:15 row_mask:0xf bank_mask:0xf
	v_fmac_f32_e32 v90, v28, v76
	v_mov_b32_e32 v91, v57
	v_fmac_f32_dpp v91, v29, v65 row_shr:2 row_mask:0xf bank_mask:0xf
	v_fmac_f32_dpp v91, v37, v65 row_shl:14 row_mask:0xf bank_mask:0xf
	v_fmac_f32_dpp v91, v29, v69 row_shr:1 row_mask:0xf bank_mask:0xf
	v_fmac_f32_dpp v91, v37, v69 row_shl:15 row_mask:0xf bank_mask:0xf
	v_fmac_f32_e32 v91, v29, v77
	v_cndmask_b32_e64 v24, v79, v39, s[8:9]
	v_mov_b32_e32 v78, v54
	v_fmac_f32_dpp v78, v34, v62 row_shr:2 row_mask:0xf bank_mask:0xf
	v_fmac_f32_dpp v78, v25, v62 row_shl:14 row_mask:0xf bank_mask:0xf
	v_fmac_f32_dpp v78, v34, v66 row_shr:1 row_mask:0xf bank_mask:0xf
	v_fmac_f32_dpp v78, v25, v66 row_shl:15 row_mask:0xf bank_mask:0xf
	s_nop 1
	v_mov_b32_dpp v25, v24 row_ror:1 row_mask:0xf bank_mask:0xf
	v_mov_b32_dpp v26, v24 row_ror:2 row_mask:0xf bank_mask:0xf
	v_mov_b32_dpp v25, v35 row_shr:1 row_mask:0xf bank_mask:0xf
	v_mov_b32_dpp v26, v35 row_shr:2 row_mask:0xf bank_mask:0xf
	v_cndmask_b32_e64 v23, v80, v40, s[8:9]
	v_fma_f32 v55, v63, v26, v55
	v_fmac_f32_e32 v55, v67, v25
	v_cndmask_b32_e64 v22, v81, v41, s[8:9]
	v_mov_b32_e32 v54, v56
	v_fmac_f32_dpp v54, v36, v64 row_shr:2 row_mask:0xf bank_mask:0xf
	v_fmac_f32_dpp v54, v23, v64 row_shl:14 row_mask:0xf bank_mask:0xf
	v_fmac_f32_dpp v54, v36, v68 row_shr:1 row_mask:0xf bank_mask:0xf
	v_fmac_f32_dpp v54, v23, v68 row_shl:15 row_mask:0xf bank_mask:0xf
	s_nop 1
	v_mov_b32_dpp v23, v22 row_ror:1 row_mask:0xf bank_mask:0xf
	v_mov_b32_dpp v24, v22 row_ror:2 row_mask:0xf bank_mask:0xf
	v_mov_b32_dpp v23, v37 row_shr:1 row_mask:0xf bank_mask:0xf
	v_mov_b32_dpp v24, v37 row_shr:2 row_mask:0xf bank_mask:0xf
	v_fmac_f32_e32 v78, v34, v74
	v_fmac_f32_e32 v57, v65, v24
	v_fmac_f32_e32 v57, v69, v23
	v_fmac_f32_e32 v55, v35, v75
	v_fmac_f32_e32 v54, v36, v76
	v_fmac_f32_e32 v57, v37, v77
	s_waitcnt vmcnt(0)
	v_mov_b32_e32 v26, v234
	v_mov_b32_e32 v27, v235
	v_mov_b32_e32 v28, v236
	v_mov_b32_e32 v29, v237
	v_mov_b32_e32 v22, v240
	v_mov_b32_e32 v23, v241
	v_mov_b32_e32 v24, v242
	v_mov_b32_e32 v25, v243
	v_add_co_u32_e32 v30, vcc, 0x2000, v200
	v_mov_b32_e32 v46, 0
	s_nop 0
	v_addc_co_u32_e32 v31, vcc, 0, v201, vcc
	v_mov_b32_e32 v34, v244
	v_mov_b32_e32 v35, v245
	v_mov_b32_e32 v36, v246
	v_mov_b32_e32 v37, v247
	v_add_co_u32_e32 v30, vcc, 0x2000, v198
	v_mov_b32_e32 v47, 0
	s_nop 0
	v_addc_co_u32_e32 v31, vcc, 0, v199, vcc
	v_mov_b32_e32 v38, v248
	v_mov_b32_e32 v39, v249
	v_mov_b32_e32 v40, v250
	v_mov_b32_e32 v41, v251
	s_and_b64 vcc, exec, s[10:11]
	v_mov_b32_e32 v62, 0
	v_mov_b32_e32 v63, 0
	v_mov_b32_e32 v64, 0
	v_mov_b32_e32 v65, 0
	s_cbranch_vccnz .LBB0_1198
	v_add_u32_e32 v31, 0xfffffa10, v227
	v_add_u32_e32 v30, 0xfffffe10, v227
	ds_read_b128 v[44:47], v31
	ds_read_b128 v[62:65], v30
